# static LDS trimmed to what the ring + bias tables need (29440 B), otherwise identical
# baseline (speedup 1.0000x reference)
	.amdhsa_kernel _Z9hymba_fwd6Params
		.amdhsa_group_segment_fixed_size 29440
		.amdhsa_private_segment_fixed_size 0
		.amdhsa_kernarg_size 424
		.amdhsa_user_sgpr_count 2
		.amdhsa_user_sgpr_dispatch_ptr 0
		.amdhsa_user_sgpr_queue_ptr 0
		.amdhsa_user_sgpr_kernarg_segment_ptr 1
		.amdhsa_user_sgpr_dispatch_id 0
		.amdhsa_user_sgpr_kernarg_preload_length 0
		.amdhsa_user_sgpr_kernarg_preload_offset 0
		.amdhsa_user_sgpr_private_segment_size 0
		.amdhsa_uses_dynamic_stack 0
		.amdhsa_enable_private_segment 0
		.amdhsa_system_sgpr_workgroup_id_x 1
		.amdhsa_system_sgpr_workgroup_id_y 0
		.amdhsa_system_sgpr_workgroup_id_z 0
		.amdhsa_system_sgpr_workgroup_info 0
		.amdhsa_system_vgpr_workitem_id 2
		.amdhsa_next_free_vgpr 256
		.amdhsa_next_free_sgpr 100
		.amdhsa_accum_offset 256
		.amdhsa_reserve_vcc 1
		.amdhsa_float_round_mode_32 0
		.amdhsa_float_round_mode_16_64 0
		.amdhsa_float_denorm_mode_32 3
		.amdhsa_float_denorm_mode_16_64 3
		.amdhsa_dx10_clamp 1
		.amdhsa_ieee_mode 1
		.amdhsa_fp16_overflow 0
		.amdhsa_tg_split 0
		.amdhsa_exception_fp_ieee_invalid_op 0
		.amdhsa_exception_fp_denorm_src 0
		.amdhsa_exception_fp_ieee_div_zero 0
		.amdhsa_exception_fp_ieee_overflow 0
		.amdhsa_exception_fp_ieee_underflow 0
		.amdhsa_exception_fp_ieee_inexact 0
		.amdhsa_exception_int_div_zero 0
	.end_amdhsa_kernel

amdhsa.kernels:
  - .agpr_count:     0
    .args:
      - .offset:         0
        .size:           168
        .value_kind:     by_value
      - .offset:         168
        .size:           4
        .value_kind:     hidden_block_count_x
      - .offset:         172
        .size:           4
        .value_kind:     hidden_block_count_y
      - .offset:         176
        .size:           4
        .value_kind:     hidden_block_count_z
      - .offset:         180
        .size:           2
        .value_kind:     hidden_group_size_x
      - .offset:         182
        .size:           2
        .value_kind:     hidden_group_size_y
      - .offset:         184
        .size:           2
        .value_kind:     hidden_group_size_z
      - .offset:         186
        .size:           2
        .value_kind:     hidden_remainder_x
      - .offset:         188
        .size:           2
        .value_kind:     hidden_remainder_y
      - .offset:         190
        .size:           2
        .value_kind:     hidden_remainder_z
      - .offset:         208
        .size:           8
        .value_kind:     hidden_global_offset_x
      - .offset:         216
        .size:           8
        .value_kind:     hidden_global_offset_y
      - .offset:         224
        .size:           8
        .value_kind:     hidden_global_offset_z
      - .offset:         232
        .size:           2
        .value_kind:     hidden_grid_dims
      - .offset:         256
        .size:           8
        .value_kind:     hidden_multigrid_sync_arg
      - .offset:         288
        .size:           4
        .value_kind:     hidden_dynamic_lds_size
    .group_segment_fixed_size: 29440
    .kernarg_segment_align: 8
    .kernarg_segment_size: 424
    .language:       OpenCL C
    .language_version:
      - 2
      - 0
    .max_flat_workgroup_size: 512
    .name:           _Z9hymba_fwd6Params
    .private_segment_fixed_size: 0
    .sgpr_count:     106
    .sgpr_spill_count: 267
    .symbol:         _Z9hymba_fwd6Params.kd
    .uniform_work_group_size: 1
    .uses_dynamic_stack: false
    .vgpr_count:     256
    .vgpr_spill_count: 0
    .wavefront_size: 64
